# same coalesced-load + lane-permute treatment for the P3/P8 sample-row GEMM
# baseline (speedup 1.0000x reference)
.LBB0_769:
	s_or_b64 exec, exec, s[42:43]
	v_add_u32_e32 v10, s22, v17
	v_ashrrev_i32_e32 v11, 31, v10
	v_or_b32_e32 v18, s21, v12
	v_lshlrev_b64 v[10:11], 11, v[10:11]
	v_ashrrev_i32_e32 v19, 31, v18
	v_lshl_add_u64 v[10:11], v[2:3], 0, v[10:11]
	v_lshlrev_b64 v[18:19], 11, v[18:19]
	v_add_co_u32_e32 v48, vcc, 0x8000, v10
	v_lshl_add_u64 v[46:47], v[4:5], 0, v[18:19]
	s_nop 0
	v_addc_co_u32_e32 v49, vcc, 0, v11, vcc
	v_add_co_u32_e32 v50, vcc, 0x8000, v46
	v_addc_co_u32_e32 v51, vcc, 0, v47, vcc
	v_and_b32_e32 v116, 63, v204
	v_lshrrev_b32_e32 v117, 2, v116
	v_and_b32_e32 v118, 15, v116
	v_lshlrev_b32_e32 v199, 2, v118
	v_lshrrev_b32_e32 v119, 4, v116
	v_add_u32_e32 v199, v199, v119
	v_lshlrev_b32_e32 v199, 2, v199
	v_sub_u32_e32 v117, v117, v118
	v_lshlrev_b32_e32 v117, 11, v117
	v_and_b32_e32 v118, 3, v116
	v_lshlrev_b32_e32 v118, 4, v118
	v_and_b32_e32 v119, 48, v116
	v_sub_u32_e32 v118, v118, v119
	v_add_u32_e32 v116, v117, v118
	v_ashrrev_i32_e32 v117, 31, v116
	v_lshl_add_u64 v[46:47], v[46:47], 0, v[116:117]
	v_lshl_add_u64 v[10:11], v[10:11], 0, v[116:117]
	v_lshl_add_u64 v[50:51], v[50:51], 0, v[116:117]
	v_lshl_add_u64 v[48:49], v[48:49], 0, v[116:117]
	global_load_dwordx4 v[52:55], v[46:47], off
	global_load_dwordx4 v[68:71], v[10:11], off
	global_load_dwordx4 v[84:87], v[50:51], off
	global_load_dwordx4 v[100:103], v[48:49], off
	global_load_dwordx4 v[56:59], v[46:47], off offset:64
	global_load_dwordx4 v[72:75], v[10:11], off offset:64
	global_load_dwordx4 v[88:91], v[50:51], off offset:64
	global_load_dwordx4 v[104:107], v[48:49], off offset:64
	global_load_dwordx4 v[60:63], v[46:47], off offset:128
	global_load_dwordx4 v[76:79], v[10:11], off offset:128
	global_load_dwordx4 v[92:95], v[50:51], off offset:128
	global_load_dwordx4 v[108:111], v[48:49], off offset:128
	global_load_dwordx4 v[64:67], v[46:47], off offset:192
	global_load_dwordx4 v[80:83], v[10:11], off offset:192
	global_load_dwordx4 v[96:99], v[50:51], off offset:192
	global_load_dwordx4 v[112:115], v[48:49], off offset:192
	v_add_u32_e32 v10, s19, v13
	s_waitcnt vmcnt(12)
	ds_bpermute_b32 v52, v199, v52
	ds_bpermute_b32 v53, v199, v53
	ds_bpermute_b32 v54, v199, v54
	ds_bpermute_b32 v55, v199, v55
	ds_bpermute_b32 v68, v199, v68
	ds_bpermute_b32 v69, v199, v69
	ds_bpermute_b32 v70, v199, v70
	ds_bpermute_b32 v71, v199, v71
	ds_bpermute_b32 v84, v199, v84
	ds_bpermute_b32 v85, v199, v85
	ds_bpermute_b32 v86, v199, v86
	ds_bpermute_b32 v87, v199, v87
	ds_bpermute_b32 v100, v199, v100
	ds_bpermute_b32 v101, v199, v101
	ds_bpermute_b32 v102, v199, v102
	ds_bpermute_b32 v103, v199, v103
	s_waitcnt lgkmcnt(0)
	v_mfma_f32_16x16x32_bf16 v[30:33], v[52:55], v[68:71], 0
	v_mfma_f32_16x16x32_bf16 v[18:21], v[52:55], v[100:103], 0
	v_mfma_f32_16x16x32_bf16 v[22:25], v[84:87], v[68:71], 0
	v_mfma_f32_16x16x32_bf16 v[26:29], v[84:87], v[100:103], 0
	s_waitcnt vmcnt(8)
	ds_bpermute_b32 v56, v199, v56
	ds_bpermute_b32 v57, v199, v57
	ds_bpermute_b32 v58, v199, v58
	ds_bpermute_b32 v59, v199, v59
	ds_bpermute_b32 v72, v199, v72
	ds_bpermute_b32 v73, v199, v73
	ds_bpermute_b32 v74, v199, v74
	ds_bpermute_b32 v75, v199, v75
	ds_bpermute_b32 v88, v199, v88
	ds_bpermute_b32 v89, v199, v89
	ds_bpermute_b32 v90, v199, v90
	ds_bpermute_b32 v91, v199, v91
	ds_bpermute_b32 v104, v199, v104
	ds_bpermute_b32 v105, v199, v105
	ds_bpermute_b32 v106, v199, v106
	ds_bpermute_b32 v107, v199, v107
	s_waitcnt lgkmcnt(0)
	v_mfma_f32_16x16x32_bf16 v[30:33], v[56:59], v[72:75], v[30:33]
	v_mfma_f32_16x16x32_bf16 v[18:21], v[56:59], v[104:107], v[18:21]
	v_mfma_f32_16x16x32_bf16 v[22:25], v[88:91], v[72:75], v[22:25]
	v_mfma_f32_16x16x32_bf16 v[26:29], v[88:91], v[104:107], v[26:29]
	s_waitcnt vmcnt(4)
	ds_bpermute_b32 v60, v199, v60
	ds_bpermute_b32 v61, v199, v61
	ds_bpermute_b32 v62, v199, v62
	ds_bpermute_b32 v63, v199, v63
	ds_bpermute_b32 v76, v199, v76
	ds_bpermute_b32 v77, v199, v77
	ds_bpermute_b32 v78, v199, v78
	ds_bpermute_b32 v79, v199, v79
	ds_bpermute_b32 v92, v199, v92
	ds_bpermute_b32 v93, v199, v93
	ds_bpermute_b32 v94, v199, v94
	ds_bpermute_b32 v95, v199, v95
	ds_bpermute_b32 v108, v199, v108
	ds_bpermute_b32 v109, v199, v109
	ds_bpermute_b32 v110, v199, v110
	ds_bpermute_b32 v111, v199, v111
	s_waitcnt lgkmcnt(0)
	v_mfma_f32_16x16x32_bf16 v[30:33], v[60:63], v[76:79], v[30:33]
	v_mfma_f32_16x16x32_bf16 v[18:21], v[60:63], v[108:111], v[18:21]
	v_mfma_f32_16x16x32_bf16 v[22:25], v[92:95], v[76:79], v[22:25]
	v_mfma_f32_16x16x32_bf16 v[26:29], v[92:95], v[108:111], v[26:29]
	s_waitcnt vmcnt(0)
	ds_bpermute_b32 v64, v199, v64
	ds_bpermute_b32 v65, v199, v65
	ds_bpermute_b32 v66, v199, v66
	ds_bpermute_b32 v67, v199, v67
	ds_bpermute_b32 v80, v199, v80
	ds_bpermute_b32 v81, v199, v81
	ds_bpermute_b32 v82, v199, v82
	ds_bpermute_b32 v83, v199, v83
	ds_bpermute_b32 v96, v199, v96
	ds_bpermute_b32 v97, v199, v97
	ds_bpermute_b32 v98, v199, v98
	ds_bpermute_b32 v99, v199, v99
	ds_bpermute_b32 v112, v199, v112
	ds_bpermute_b32 v113, v199, v113
	ds_bpermute_b32 v114, v199, v114
	ds_bpermute_b32 v115, v199, v115
	s_waitcnt lgkmcnt(0)
	v_mfma_f32_16x16x32_bf16 v[30:33], v[64:67], v[80:83], v[30:33]
	v_mfma_f32_16x16x32_bf16 v[18:21], v[64:67], v[112:115], v[18:21]
	v_mfma_f32_16x16x32_bf16 v[22:25], v[96:99], v[80:83], v[22:25]
	v_mfma_f32_16x16x32_bf16 v[26:29], v[96:99], v[112:115], v[26:29]
	s_nop 7
	s_nop 1
	ds_write_b128 v10, v[30:33]
	s_nop 0
	ds_write_b128 v10, v[18:21] offset:2048
	s_nop 1
	ds_write_b128 v10, v[22:25] offset:1024
	ds_write_b128 v10, v[26:29] offset:3072
	s_waitcnt lgkmcnt(0)
	s_barrier
	s_and_saveexec_b64 s[42:43], s[0:1]
	s_cbranch_execz .LBB0_766
	v_lshlrev_b32_e32 v22, 16, v8
	v_and_b32_e32 v23, 0xffff0000, v8
	v_lshlrev_b32_e32 v24, 16, v9
	v_and_b32_e32 v25, 0xffff0000, v9
	ds_read_b128 v[8:11], v14
	ds_read_b128 v[18:21], v15 offset:4096
	s_andn2_b64 vcc, exec, s[94:95]
	s_waitcnt lgkmcnt(0)
	v_pk_add_f32 v[20:21], v[10:11], v[20:21]
	v_pk_add_f32 v[18:19], v[8:9], v[18:19]
	ds_read_b128 v[8:11], v15 offset:8192
	s_waitcnt lgkmcnt(0)
	v_pk_add_f32 v[20:21], v[20:21], v[10:11]
	v_pk_add_f32 v[18:19], v[18:19], v[8:9]
	ds_read_b128 v[8:11], v15 offset:12288
	s_waitcnt lgkmcnt(0)
	v_pk_add_f32 v[20:21], v[20:21], v[10:11]
	v_pk_add_f32 v[18:19], v[18:19], v[8:9]
	ds_read_b128 v[8:11], v15 offset:16384
	s_waitcnt lgkmcnt(0)
	v_pk_add_f32 v[20:21], v[20:21], v[10:11]
	v_pk_add_f32 v[18:19], v[18:19], v[8:9]
	ds_read_b128 v[8:11], v15 offset:20480
	s_waitcnt lgkmcnt(0)
	v_pk_add_f32 v[20:21], v[20:21], v[10:11]
	v_pk_add_f32 v[18:19], v[18:19], v[8:9]
	ds_read_b128 v[8:11], v15 offset:24576
	s_waitcnt lgkmcnt(0)
	v_pk_add_f32 v[20:21], v[20:21], v[10:11]
	v_pk_add_f32 v[18:19], v[18:19], v[8:9]
	ds_read_b128 v[8:11], v15 offset:28672
	s_waitcnt lgkmcnt(0)
	v_pk_add_f32 v[10:11], v[20:21], v[10:11]
	v_pk_add_f32 v[18:19], v[18:19], v[8:9]
	v_pk_add_f32 v[8:9], v[10:11], v[24:25]
	v_pk_add_f32 v[10:11], v[18:19], v[22:23]
	s_cbranch_vccnz .LBB0_772
	v_lshlrev_b64 v[18:19], 11, v[6:7]
	v_add_u32_e32 v20, s21, v0
	v_ashrrev_i32_e32 v21, 31, v20
	v_lshl_add_u64 v[18:19], s[64:65], 0, v[18:19]
	v_lshl_add_u64 v[18:19], v[20:21], 1, v[18:19]
	v_cvt_pk_bf16_f32 v20, v10, v11
	v_cvt_pk_bf16_f32 v21, v8, v9
	global_store_dwordx2 v[18:19], v[20:21], off
